# attention neighbourhood chunks: 16 unconditional bias-table LDS lookups with one wait and mask select instead of 16 branchy serial lookups
# baseline (speedup 1.0000x reference)
.LBB0_324:
	v_add_u32_e32 v118, 0, v161
	ds_read_b128 v[120:123], v118
	v_add_u32_e32 v117, 0, v160
	ds_read_b128 v[124:127], v117
	v_mov_b32_e32 v114, v192
	s_waitcnt vmcnt(27) lgkmcnt(1)
	v_mfma_f32_16x16x32_bf16 v[120:123], v[120:123], v[2:5], 0
	s_waitcnt vmcnt(26) lgkmcnt(0)
	v_mfma_f32_16x16x32_bf16 v[120:123], v[124:127], v[6:9], v[120:123]
	ds_read_b128 v[124:127], v118 offset:2048
	ds_read_b128 v[176:179], v117 offset:2048
	s_waitcnt lgkmcnt(1)
	v_mfma_f32_16x16x32_bf16 v[124:127], v[124:127], v[2:5], 0
	s_nop 3
	v_mul_f32_e32 v116, 0x3e000000, v120
	v_mul_f32_e32 v119, 0x3e000000, v121
	v_max3_f32 v116, v116, v174, v119
	s_waitcnt lgkmcnt(0)
	v_mfma_f32_16x16x32_bf16 v[124:127], v[176:179], v[6:9], v[124:127]
	ds_read_b128 v[176:179], v118 offset:4096
	ds_read_b128 v[180:183], v117 offset:4096
	v_mul_f32_e32 v119, 0x3e000000, v122
	v_mul_f32_e32 v128, 0x3e000000, v123
	s_waitcnt lgkmcnt(1)
	v_mfma_f32_16x16x32_bf16 v[176:179], v[176:179], v[2:5], 0
	v_max3_f32 v116, v116, v119, v128
	s_nop 0
	v_mul_f32_e32 v119, 0x3e000000, v124
	v_mul_f32_e32 v128, 0x3e000000, v125
	s_waitcnt lgkmcnt(0)
	v_mfma_f32_16x16x32_bf16 v[184:187], v[180:183], v[6:9], v[176:179]
	s_nop 2
	ds_read_b128 v[176:179], v118 offset:6144
	ds_read_b128 v[180:183], v117 offset:6144
	v_max3_f32 v116, v116, v119, v128
	v_mul_f32_e32 v119, 0x3e000000, v126
	s_waitcnt lgkmcnt(1)
	v_mfma_f32_16x16x32_bf16 v[176:179], v[176:179], v[2:5], 0
	v_mul_f32_e32 v128, 0x3e000000, v127
	v_max3_f32 v116, v116, v119, v128
	v_mul_f32_e32 v119, 0x3e000000, v184
	s_waitcnt lgkmcnt(0)
	v_mfma_f32_16x16x32_bf16 v[188:191], v[180:183], v[6:9], v[176:179]
	v_mul_f32_e32 v128, 0x3e000000, v185
	v_max3_f32 v116, v116, v119, v128
	v_mul_f32_e32 v119, 0x3e000000, v186
	v_mul_f32_e32 v128, 0x3e000000, v187
	v_max3_f32 v116, v116, v119, v128
	s_nop 2
	v_mul_f32_e32 v119, 0x3e000000, v188
	v_mul_f32_e32 v128, 0x3e000000, v189
	v_max3_f32 v116, v116, v119, v128
	v_mul_f32_e32 v119, 0x3e000000, v190
	v_mul_f32_e32 v128, 0x3e000000, v191
	v_max3_f32 v116, v116, v119, v128
	ds_bpermute_b32 v119, v146, v116
	s_waitcnt lgkmcnt(0)
	v_max_f32_e32 v119, v119, v119
	v_max_f32_e32 v116, v116, v119
	ds_bpermute_b32 v119, v145, v116
	s_waitcnt lgkmcnt(0)
	v_max3_f32 v162, v115, v116, v119
	v_fma_f32 v116, v120, s33, -v162
	v_mul_f32_e32 v116, 0x3fb8aa3b, v116
	v_exp_f32_e32 v176, v116
	v_fma_f32 v116, v121, s33, -v162
	v_mul_f32_e32 v116, 0x3fb8aa3b, v116
	v_exp_f32_e32 v177, v116
	v_fma_f32 v116, v122, s33, -v162
	v_mul_f32_e32 v116, 0x3fb8aa3b, v116
	v_exp_f32_e32 v178, v116
	v_fma_f32 v116, v123, s33, -v162
	v_mul_f32_e32 v116, 0x3fb8aa3b, v116
	v_exp_f32_e32 v179, v116
	v_fma_f32 v116, v124, s33, -v162
	v_mul_f32_e32 v116, 0x3fb8aa3b, v116
	v_sub_f32_e32 v115, v115, v162
	v_exp_f32_e32 v180, v116
	v_fma_f32 v116, v125, s33, -v162
	v_mul_f32_e32 v115, 0x3fb8aa3b, v115
	v_mul_f32_e32 v116, 0x3fb8aa3b, v116
	v_exp_f32_e32 v181, v116
	v_fma_f32 v116, v126, s33, -v162
	v_exp_f32_e32 v142, v115
	v_add_u32_e32 v115, 0, v157
	v_mul_f32_e32 v116, 0x3fb8aa3b, v116
	v_add_u32_e32 v119, 0x8000, v115
	v_exp_f32_e32 v182, v116
	v_fma_f32 v116, v127, s33, -v162
	ds_read2_b64 v[124:127], v119 offset1:4
	v_mul_f32_e32 v116, 0x3fb8aa3b, v116
	v_exp_f32_e32 v183, v116
	v_pk_mul_f32 v[112:113], v[112:113], v[142:143] op_sel_hi:[1,0]
	v_pk_mul_f32 v[110:111], v[110:111], v[142:143] op_sel_hi:[1,0]
	v_cvt_pk_bf16_f32 v120, v176, v177
	v_cvt_pk_bf16_f32 v121, v178, v179
	v_cvt_pk_bf16_f32 v122, v180, v181
	v_cvt_pk_bf16_f32 v123, v182, v183
	v_add_u32_e32 v128, 0xa000, v115
	v_fma_f32 v116, v184, s33, -v162
	s_waitcnt lgkmcnt(0)
	v_mfma_f32_16x16x32_bf16 v[110:113], v[124:127], v[120:123], v[110:113]
	ds_read2_b64 v[124:127], v128 offset0:32 offset1:36
	v_mul_f32_e32 v116, 0x3fb8aa3b, v116
	v_exp_f32_e32 v184, v116
	v_fma_f32 v116, v185, s33, -v162
	v_mul_f32_e32 v116, 0x3fb8aa3b, v116
	v_exp_f32_e32 v185, v116
	v_fma_f32 v116, v186, s33, -v162
	v_mul_f32_e32 v116, 0x3fb8aa3b, v116
	v_exp_f32_e32 v186, v116
	v_fma_f32 v116, v187, s33, -v162
	v_mul_f32_e32 v116, 0x3fb8aa3b, v116
	v_exp_f32_e32 v187, v116
	v_fma_f32 v116, v188, s33, -v162
	v_pk_mul_f32 v[108:109], v[108:109], v[142:143] op_sel_hi:[1,0]
	v_pk_mul_f32 v[106:107], v[106:107], v[142:143] op_sel_hi:[1,0]
	v_add_u32_e32 v129, 0xc000, v115
	v_mul_f32_e32 v116, 0x3fb8aa3b, v116
	s_waitcnt lgkmcnt(0)
	v_mfma_f32_16x16x32_bf16 v[106:109], v[124:127], v[120:123], v[106:109]
	ds_read2_b64 v[124:127], v129 offset0:64 offset1:68
	v_exp_f32_e32 v188, v116
	v_fma_f32 v116, v189, s33, -v162
	v_mul_f32_e32 v116, 0x3fb8aa3b, v116
	v_exp_f32_e32 v189, v116
	v_fma_f32 v116, v190, s33, -v162
	v_mul_f32_e32 v116, 0x3fb8aa3b, v116
	v_exp_f32_e32 v190, v116
	v_fma_f32 v116, v191, s33, -v162
	v_mul_f32_e32 v116, 0x3fb8aa3b, v116
	v_exp_f32_e32 v191, v116
	v_add_u32_e32 v116, 0, v156
	v_pk_mul_f32 v[104:105], v[104:105], v[142:143] op_sel_hi:[1,0]
	v_pk_mul_f32 v[102:103], v[102:103], v[142:143] op_sel_hi:[1,0]
	v_add_u32_e32 v144, 0x8000, v116
	v_pk_mul_f32 v[100:101], v[100:101], v[142:143] op_sel_hi:[1,0]
	s_waitcnt lgkmcnt(0)
	v_mfma_f32_16x16x32_bf16 v[102:105], v[124:127], v[120:123], v[102:105]
	ds_read2_b64 v[124:127], v144 offset1:4
	v_pk_mul_f32 v[98:99], v[98:99], v[142:143] op_sel_hi:[1,0]
	s_waitcnt lgkmcnt(0)
	s_nop 0
	v_mfma_f32_16x16x32_bf16 v[98:101], v[124:127], v[120:123], v[98:101]
	ds_read2_b64 v[124:127], v119 offset0:8 offset1:12
	v_cvt_pk_bf16_f32 v120, v184, v185
	v_cvt_pk_bf16_f32 v121, v186, v187
	v_cvt_pk_bf16_f32 v122, v188, v189
	v_cvt_pk_bf16_f32 v123, v190, v191
	v_add_u32_e32 v119, 0x10400, v118
	s_waitcnt lgkmcnt(0)
	v_mfma_f32_16x16x32_bf16 v[110:113], v[124:127], v[120:123], v[110:113]
	ds_read2_b64 v[124:127], v128 offset0:40 offset1:44
	s_waitcnt lgkmcnt(0)
	v_mfma_f32_16x16x32_bf16 v[106:109], v[124:127], v[120:123], v[106:109]
	ds_read2_b64 v[124:127], v129 offset0:72 offset1:76
	s_waitcnt lgkmcnt(0)
	v_mfma_f32_16x16x32_bf16 v[102:105], v[124:127], v[120:123], v[102:105]
	ds_read2_b64 v[124:127], v144 offset0:8 offset1:12
	s_waitcnt lgkmcnt(0)
	v_mfma_f32_16x16x32_bf16 v[98:101], v[124:127], v[120:123], v[98:101]
	ds_read_b128 v[120:123], v119
	v_add_u32_e32 v119, 0x10400, v117
	ds_read_b128 v[124:127], v119
	s_waitcnt vmcnt(1) lgkmcnt(1)
	v_mfma_f32_16x16x32_bf16 v[120:123], v[120:123], v[54:57], 0
	v_add_u32_e32 v119, 0x10c00, v118
	s_waitcnt vmcnt(0) lgkmcnt(0)
	v_mfma_f32_16x16x32_bf16 v[120:123], v[124:127], v[58:61], v[120:123]
	ds_read_b128 v[124:127], v119
	v_add_u32_e32 v119, 0x10c00, v117
	ds_read_b128 v[212:215], v119
	s_waitcnt lgkmcnt(1)
	v_mfma_f32_16x16x32_bf16 v[124:127], v[124:127], v[54:57], 0
	v_add_u32_e32 v119, 0x11400, v118
	v_add_u32_e32 v118, 0x11c00, v118
	s_waitcnt lgkmcnt(0)
	v_mfma_f32_16x16x32_bf16 v[124:127], v[212:215], v[58:61], v[124:127]
	ds_read_b128 v[212:215], v119
	v_add_u32_e32 v119, 0x11400, v117
	ds_read_b128 v[216:219], v119
	s_waitcnt lgkmcnt(1)
	v_mfma_f32_16x16x32_bf16 v[212:215], v[212:215], v[54:57], 0
	v_add_u32_e32 v117, 0x11c00, v117
	v_mul_f32_e32 v119, 0x3e000000, v123
	s_waitcnt lgkmcnt(0)
	v_mfma_f32_16x16x32_bf16 v[220:223], v[216:219], v[58:61], v[212:215]
	ds_read_b128 v[216:219], v117
	v_mul_f32_e32 v117, 0x3e000000, v120
	s_nop 1
	ds_read_b128 v[212:215], v118
	s_waitcnt lgkmcnt(0)
	v_mfma_f32_16x16x32_bf16 v[212:215], v[212:215], v[54:57], 0
	v_mul_f32_e32 v118, 0x3e000000, v121
	v_max3_f32 v117, v117, v174, v118
	v_mul_f32_e32 v118, 0x3e000000, v122
	v_mfma_f32_16x16x32_bf16 v[224:227], v[216:219], v[58:61], v[212:215]
	v_max3_f32 v117, v117, v118, v119
	v_mul_f32_e32 v118, 0x3e000000, v124
	v_mul_f32_e32 v119, 0x3e000000, v125
	v_max3_f32 v117, v117, v118, v119
	v_mul_f32_e32 v118, 0x3e000000, v126
	v_mul_f32_e32 v119, 0x3e000000, v127
	v_max3_f32 v117, v117, v118, v119
	v_mul_f32_e32 v118, 0x3e000000, v220
	v_mul_f32_e32 v119, 0x3e000000, v221
	v_max3_f32 v117, v117, v118, v119
	v_mul_f32_e32 v118, 0x3e000000, v222
	v_mul_f32_e32 v119, 0x3e000000, v223
	v_max3_f32 v117, v117, v118, v119
	v_mul_f32_e32 v118, 0x3e000000, v224
	v_mul_f32_e32 v119, 0x3e000000, v225
	v_max3_f32 v117, v117, v118, v119
	v_mul_f32_e32 v118, 0x3e000000, v226
	v_mul_f32_e32 v119, 0x3e000000, v227
	v_max3_f32 v117, v117, v118, v119
	ds_bpermute_b32 v118, v146, v117
	s_waitcnt lgkmcnt(0)
	v_max_f32_e32 v118, v118, v118
	v_max_f32_e32 v117, v117, v118
	ds_bpermute_b32 v118, v145, v117
	s_waitcnt lgkmcnt(0)
	v_max3_f32 v192, v114, v117, v118
	v_fma_f32 v117, v120, s33, -v192
	v_mul_f32_e32 v117, 0x3fb8aa3b, v117
	v_exp_f32_e32 v193, v117
	v_fma_f32 v117, v121, s33, -v192
	v_mul_f32_e32 v117, 0x3fb8aa3b, v117
	v_exp_f32_e32 v212, v117
	v_fma_f32 v117, v122, s33, -v192
	v_mul_f32_e32 v117, 0x3fb8aa3b, v117
	v_exp_f32_e32 v213, v117
	v_fma_f32 v117, v123, s33, -v192
	v_mul_f32_e32 v117, 0x3fb8aa3b, v117
	v_sub_f32_e32 v114, v114, v192
	v_exp_f32_e32 v214, v117
	v_fma_f32 v117, v124, s33, -v192
	v_mul_f32_e32 v114, 0x3fb8aa3b, v114
	v_mul_f32_e32 v117, 0x3fb8aa3b, v117
	v_exp_f32_e32 v215, v117
	v_fma_f32 v117, v125, s33, -v192
	v_exp_f32_e32 v144, v114
	v_add_u32_e32 v114, 0x18400, v115
	v_mul_f32_e32 v117, 0x3fb8aa3b, v117
	ds_read_b64 v[122:123], v114
	v_add_u32_e32 v114, 0x18420, v115
	v_exp_f32_e32 v216, v117
	v_fma_f32 v117, v126, s33, -v192
	ds_read_b64 v[124:125], v114
	v_mul_f32_e32 v117, 0x3fb8aa3b, v117
	v_exp_f32_e32 v217, v117
	v_fma_f32 v117, v127, s33, -v192
	v_mul_f32_e32 v117, 0x3fb8aa3b, v117
	v_exp_f32_e32 v218, v117
	v_pk_mul_f32 v[84:85], v[84:85], v[144:145] op_sel_hi:[1,0]
	v_pk_mul_f32 v[82:83], v[82:83], v[144:145] op_sel_hi:[1,0]
	v_cvt_pk_bf16_f32 v118, v193, v212
	v_cvt_pk_bf16_f32 v119, v213, v214
	v_cvt_pk_bf16_f32 v120, v215, v216
	v_cvt_pk_bf16_f32 v121, v217, v218
	v_add_u32_e32 v114, 0x1a500, v115
	v_pk_mul_f32 v[88:89], v[88:89], v[144:145] op_sel_hi:[1,0]
	s_waitcnt lgkmcnt(0)
	v_mfma_f32_16x16x32_bf16 v[82:85], v[122:125], v[118:121], v[82:85]
	ds_read_b64 v[122:123], v114
	v_add_u32_e32 v114, 0x1a520, v115
	ds_read_b64 v[124:125], v114
	v_pk_mul_f32 v[86:87], v[86:87], v[144:145] op_sel_hi:[1,0]
	v_add_u32_e32 v114, 0x1c600, v115
	v_fma_f32 v117, v220, s33, -v192
	s_waitcnt lgkmcnt(0)
	v_mfma_f32_16x16x32_bf16 v[86:89], v[122:125], v[118:121], v[86:89]
	ds_read_b64 v[122:123], v114
	v_add_u32_e32 v114, 0x1c620, v115
	ds_read_b64 v[124:125], v114
	v_pk_mul_f32 v[92:93], v[92:93], v[144:145] op_sel_hi:[1,0]
	v_pk_mul_f32 v[90:91], v[90:91], v[144:145] op_sel_hi:[1,0]
	v_add_u32_e32 v114, 0x18400, v116
	v_mul_f32_e32 v117, 0x3fb8aa3b, v117
	s_waitcnt lgkmcnt(0)
	v_mfma_f32_16x16x32_bf16 v[90:93], v[122:125], v[118:121], v[90:93]
	ds_read_b64 v[122:123], v114
	v_add_u32_e32 v114, 0x18420, v116
	v_exp_f32_e32 v219, v117
	v_fma_f32 v117, v221, s33, -v192
	ds_read_b64 v[124:125], v114
	v_mul_f32_e32 v117, 0x3fb8aa3b, v117
	v_exp_f32_e32 v220, v117
	v_fma_f32 v117, v222, s33, -v192
	v_mul_f32_e32 v117, 0x3fb8aa3b, v117
	v_exp_f32_e32 v221, v117
	v_fma_f32 v117, v223, s33, -v192
	v_mul_f32_e32 v117, 0x3fb8aa3b, v117
	v_exp_f32_e32 v222, v117
	v_fma_f32 v117, v224, s33, -v192
	v_mul_f32_e32 v117, 0x3fb8aa3b, v117
	v_exp_f32_e32 v223, v117
	v_fma_f32 v117, v225, s33, -v192
	v_pk_mul_f32 v[96:97], v[96:97], v[144:145] op_sel_hi:[1,0]
	v_pk_mul_f32 v[94:95], v[94:95], v[144:145] op_sel_hi:[1,0]
	v_add_u32_e32 v114, 0x18440, v115
	v_mul_f32_e32 v117, 0x3fb8aa3b, v117
	s_waitcnt lgkmcnt(0)
	v_mfma_f32_16x16x32_bf16 v[94:97], v[122:125], v[118:121], v[94:97]
	ds_read_b64 v[122:123], v114
	v_add_u32_e32 v114, 0x18460, v115
	v_exp_f32_e32 v224, v117
	v_fma_f32 v117, v226, s33, -v192
	ds_read_b64 v[124:125], v114
	v_mul_f32_e32 v117, 0x3fb8aa3b, v117
	v_exp_f32_e32 v225, v117
	v_fma_f32 v117, v227, s33, -v192
	v_mul_f32_e32 v117, 0x3fb8aa3b, v117
	v_exp_f32_e32 v226, v117
	v_cvt_pk_bf16_f32 v118, v219, v220
	v_cvt_pk_bf16_f32 v119, v221, v222
	v_cvt_pk_bf16_f32 v120, v223, v224
	v_cvt_pk_bf16_f32 v121, v225, v226
	v_add_u32_e32 v114, 0x1a540, v115
	s_waitcnt lgkmcnt(0)
	v_mfma_f32_16x16x32_bf16 v[82:85], v[122:125], v[118:121], v[82:85]
	ds_read_b64 v[122:123], v114
	v_add_u32_e32 v114, 0x1a560, v115
	ds_read_b64 v[124:125], v114
	v_add_u32_e32 v114, 0x1c640, v115
	s_waitcnt lgkmcnt(0)
	v_mfma_f32_16x16x32_bf16 v[86:89], v[122:125], v[118:121], v[86:89]
	ds_read_b64 v[122:123], v114
	v_add_u32_e32 v114, 0x1c660, v115
	ds_read_b64 v[124:125], v114
	v_add_u32_e32 v114, 0x18440, v116
	v_add_u32_e32 v116, 0x18460, v116
	ds_read_b64 v[114:115], v114
	ds_read_b64 v[116:117], v116
	s_waitcnt lgkmcnt(2)
	v_mfma_f32_16x16x32_bf16 v[90:93], v[122:125], v[118:121], v[90:93]
	s_waitcnt lgkmcnt(0)
	v_mfma_f32_16x16x32_bf16 v[94:97], v[114:117], v[118:121], v[94:97]
	v_mfma_f32_16x16x32_bf16 v[114:117], v[10:13], v[2:5], 0
	v_add_u32_e32 v229, 0, v155
	v_mov_b32_e32 v227, 0xff800000
	v_mfma_f32_16x16x32_bf16 v[126:129], v[14:17], v[6:9], v[114:117]
	v_mfma_f32_16x16x32_bf16 v[114:117], v[18:21], v[2:5], 0
	v_mfma_f32_16x16x32_bf16 v[122:125], v[22:25], v[6:9], v[114:117]
	v_mfma_f32_16x16x32_bf16 v[114:117], v[26:29], v[2:5], 0
	v_mfma_f32_16x16x32_bf16 v[118:121], v[30:33], v[6:9], v[114:117]
	v_mfma_f32_16x16x32_bf16 v[114:117], v[34:37], v[2:5], 0
	v_mfma_f32_16x16x32_bf16 v[114:117], v[38:41], v[6:9], v[114:117]
	v_mov_b32_e32 v251, 0xff800000
	v_add_u32_e32 v234, 0x20b64, v155
	ds_read_b32 v234, v234
	v_add_u32_e32 v235, 0x20b64, v154
	ds_read_b32 v235, v235
	v_add_u32_e32 v236, 0x20b64, v153
	ds_read_b32 v236, v236
	v_add_u32_e32 v238, 0x20b64, v152
	ds_read_b32 v238, v238
	v_add_u32_e32 v239, 0x20b64, v151
	ds_read_b32 v239, v239
	v_add_u32_e32 v240, 0x20b64, v150
	ds_read_b32 v240, v240
	v_add_u32_e32 v241, 0x20b64, v149
	ds_read_b32 v241, v241
	v_add_u32_e32 v242, 0x20b64, v148
	ds_read_b32 v242, v242
	v_add_u32_e32 v243, 0x20be0, v155
	ds_read_b32 v243, v243
	v_add_u32_e32 v244, 0x20be0, v154
	ds_read_b32 v244, v244
	v_add_u32_e32 v245, 0x20be0, v153
	ds_read_b32 v245, v245
	v_add_u32_e32 v246, 0x20be0, v152
	ds_read_b32 v246, v246
	v_add_u32_e32 v247, 0x20be0, v151
	ds_read_b32 v247, v247
	v_add_u32_e32 v248, 0x20be0, v150
	ds_read_b32 v248, v248
	v_add_u32_e32 v249, 0x20be0, v149
	ds_read_b32 v249, v249
	v_add_u32_e32 v250, 0x20be0, v148
	ds_read_b32 v250, v250
	s_waitcnt lgkmcnt(0)
	v_fmac_f32_e32 v234, 0x3e000000, v126
	v_fmac_f32_e32 v235, 0x3e000000, v127
	v_fmac_f32_e32 v236, 0x3e000000, v128
	v_fmac_f32_e32 v238, 0x3e000000, v129
	v_fmac_f32_e32 v239, 0x3e000000, v122
	v_fmac_f32_e32 v240, 0x3e000000, v123
	v_fmac_f32_e32 v241, 0x3e000000, v124
	v_fmac_f32_e32 v242, 0x3e000000, v125
	v_fmac_f32_e32 v243, 0x3e000000, v118
	v_fmac_f32_e32 v244, 0x3e000000, v119
	v_fmac_f32_e32 v245, 0x3e000000, v120
	v_fmac_f32_e32 v246, 0x3e000000, v121
	v_fmac_f32_e32 v247, 0x3e000000, v114
	v_fmac_f32_e32 v248, 0x3e000000, v115
	v_fmac_f32_e32 v249, 0x3e000000, v116
	v_fmac_f32_e32 v250, 0x3e000000, v117
	v_cndmask_b32_e64 v227, v251, v234, s[6:7]
	v_cndmask_b32_e64 v228, v251, v235, s[8:9]
	v_cndmask_b32_e64 v126, v251, v236, s[10:11]
	v_cndmask_b32_e64 v128, v251, v238, s[16:17]
	v_cndmask_b32_e64 v127, v251, v239, s[18:19]
	v_cndmask_b32_e64 v129, v251, v240, s[30:31]
	v_cndmask_b32_e64 v122, v251, v241, s[40:41]
	v_cndmask_b32_e64 v123, v251, v242, s[38:39]
	v_cndmask_b32_e64 v124, v251, v243, s[6:7]
	v_cndmask_b32_e64 v125, v251, v244, s[8:9]
	v_cndmask_b32_e64 v229, v251, v245, s[10:11]
	v_cndmask_b32_e64 v231, v251, v246, s[16:17]
	v_cndmask_b32_e64 v230, v251, v247, s[18:19]
	v_cndmask_b32_e64 v114, v251, v248, s[30:31]
	v_cndmask_b32_e64 v233, v251, v249, s[40:41]
	v_cndmask_b32_e64 v232, v251, v250, s[38:39]
	s_mov_b32 s12, 0xff800000
	v_max3_f32 v115, v227, s12, v228
	v_max3_f32 v115, v115, v126, v128
	v_max3_f32 v115, v115, v127, v129
	v_max3_f32 v115, v115, v122, v123
	v_max3_f32 v115, v115, v124, v125
	v_max3_f32 v115, v115, v229, v231
	v_max3_f32 v115, v115, v230, v114
	v_max3_f32 v115, v115, v233, v232
	ds_bpermute_b32 v116, v146, v115
	s_cmpk_eq_i32 s3, 0x180
	s_waitcnt lgkmcnt(0)
	v_max_f32_e32 v116, v116, v116
	v_max_f32_e32 v115, v115, v116
	ds_bpermute_b32 v116, v145, v115
	s_waitcnt lgkmcnt(0)
	v_max3_f32 v115, v162, v115, v116
	v_sub_f32_e32 v116, v162, v115
	v_sub_f32_e32 v117, v227, v115
	v_sub_f32_e32 v118, v228, v115
	v_sub_f32_e32 v119, v126, v115
	v_mul_f32_e32 v162, 0x3fb8aa3b, v116
	v_mul_f32_e32 v116, 0x3fb8aa3b, v117
	v_mul_f32_e32 v117, 0x3fb8aa3b, v118
	v_mul_f32_e32 v118, 0x3fb8aa3b, v119
	v_sub_f32_e32 v119, v128, v115
	v_sub_f32_e32 v120, v127, v115
	v_sub_f32_e32 v121, v129, v115
	v_sub_f32_e32 v122, v122, v115
	v_sub_f32_e32 v123, v123, v115
	v_sub_f32_e32 v114, v114, v115
	v_mul_f32_e32 v119, 0x3fb8aa3b, v119
	v_mul_f32_e32 v120, 0x3fb8aa3b, v120
	v_mul_f32_e32 v121, 0x3fb8aa3b, v121
	v_mul_f32_e32 v122, 0x3fb8aa3b, v122
	v_mul_f32_e32 v123, 0x3fb8aa3b, v123
	v_mul_f32_e32 v114, 0x3fb8aa3b, v114
	v_exp_f32_e32 v116, v116
	v_exp_f32_e32 v117, v117
	v_exp_f32_e32 v118, v118
	v_exp_f32_e32 v119, v119
	v_exp_f32_e32 v120, v120
	v_exp_f32_e32 v121, v121
	v_exp_f32_e32 v122, v122
	v_exp_f32_e32 v123, v123
	v_exp_f32_e32 v129, v114
	v_exp_f32_e32 v114, v162
	v_sub_f32_e32 v162, v233, v115
	v_mul_f32_e32 v162, 0x3fb8aa3b, v162
	v_sub_f32_e32 v124, v124, v115
	v_sub_f32_e32 v125, v125, v115
	v_sub_f32_e32 v126, v229, v115
	v_sub_f32_e32 v127, v231, v115
	v_sub_f32_e32 v128, v230, v115
	v_exp_f32_e32 v227, v162
	v_sub_f32_e32 v162, v232, v115
	v_mul_f32_e32 v124, 0x3fb8aa3b, v124
	v_mul_f32_e32 v125, 0x3fb8aa3b, v125
	v_mul_f32_e32 v126, 0x3fb8aa3b, v126
	v_mul_f32_e32 v127, 0x3fb8aa3b, v127
	v_mul_f32_e32 v128, 0x3fb8aa3b, v128
	v_mul_f32_e32 v162, 0x3fb8aa3b, v162
	v_exp_f32_e32 v124, v124
	v_exp_f32_e32 v125, v125
	v_exp_f32_e32 v126, v126
	v_exp_f32_e32 v127, v127
	v_exp_f32_e32 v128, v128
	v_pk_mul_f32 v[112:113], v[112:113], v[114:115] op_sel_hi:[1,0]
	v_pk_mul_f32 v[110:111], v[110:111], v[114:115] op_sel_hi:[1,0]
	v_cvt_pk_bf16_f32 v234, v116, v117
	v_cvt_pk_bf16_f32 v235, v118, v119
	v_cvt_pk_bf16_f32 v236, v120, v121
	v_cvt_pk_bf16_f32 v237, v122, v123
	v_pk_mul_f32 v[108:109], v[108:109], v[114:115] op_sel_hi:[1,0]
	v_pk_mul_f32 v[106:107], v[106:107], v[114:115] op_sel_hi:[1,0]
	v_pk_mul_f32 v[104:105], v[104:105], v[114:115] op_sel_hi:[1,0]
	v_pk_mul_f32 v[102:103], v[102:103], v[114:115] op_sel_hi:[1,0]
	v_exp_f32_e32 v228, v162
	v_pk_mul_f32 v[100:101], v[100:101], v[114:115] op_sel_hi:[1,0]
	v_pk_mul_f32 v[98:99], v[98:99], v[114:115] op_sel_hi:[1,0]
	v_mfma_f32_16x16x32_bf16 v[110:113], v[42:45], v[234:237], v[110:113]
	v_cvt_pk_bf16_f32 v230, v124, v125
	v_cvt_pk_bf16_f32 v231, v126, v127
	v_cvt_pk_bf16_f32 v232, v128, v129
	v_mfma_f32_16x16x32_bf16 v[106:109], v[46:49], v[234:237], v[106:109]
	v_cvt_pk_bf16_f32 v233, v227, v228
	v_mfma_f32_16x16x32_bf16 v[102:105], v[50:53], v[234:237], v[102:105]
	v_mfma_f32_16x16x32_bf16 v[98:101], v[62:65], v[234:237], v[98:101]
	v_mfma_f32_16x16x32_bf16 v[110:113], v[66:69], v[230:233], v[110:113]
	v_mfma_f32_16x16x32_bf16 v[106:109], v[70:73], v[230:233], v[106:109]
	v_mfma_f32_16x16x32_bf16 v[102:105], v[74:77], v[230:233], v[102:105]
	v_mfma_f32_16x16x32_bf16 v[98:101], v[78:81], v[230:233], v[98:101]
	s_cbranch_scc1 .LBB0_356
	v_add_u32_e32 v70, s3, v158
	v_add_u32_e32 v44, 0x1080, v70
	v_ashrrev_i32_e32 v42, 5, v44
	v_add_u32_e32 v45, 0x1090, v70
	v_ashrrev_i32_e32 v43, 31, v42
	v_lshlrev_b64 v[48:49], 12, v[42:43]
	v_ashrrev_i32_e32 v42, 5, v45
	v_and_b32_e32 v44, 31, v44
	v_ashrrev_i32_e32 v43, 31, v42
	v_add_u32_e32 v34, s3, v159
	v_lshlrev_b64 v[52:53], 12, v[42:43]
	v_and_b32_e32 v45, 31, v45
	v_lshl_add_u64 v[42:43], v[134:135], 0, v[48:49]
	v_lshlrev_b32_e32 v162, 1, v44
	v_add_u32_e32 v10, 0x1080, v34
	v_add_u32_e32 v18, 0x1090, v34
	v_add_u32_e32 v26, 0x10c0, v34
	v_add_u32_e32 v34, 0x10d0, v34
	v_lshl_add_u64 v[50:51], v[42:43], 0, v[162:163]
	v_lshl_add_u64 v[42:43], v[134:135], 0, v[52:53]
	v_lshlrev_b32_e32 v62, 1, v45
	v_mov_b32_e32 v63, v163
	v_lshl_add_u64 v[48:49], v[136:137], 0, v[48:49]
	v_mad_i64_i32 v[14:15], s[12:13], v10, s23, v[132:133]
	v_mad_i64_i32 v[22:23], s[12:13], v18, s23, v[132:133]
	v_mad_i64_i32 v[30:31], s[12:13], v26, s23, v[132:133]
	v_mad_i64_i32 v[38:39], s[12:13], v34, s23, v[132:133]
	v_lshl_add_u64 v[64:65], v[42:43], 0, v[62:63]
	v_lshl_add_u64 v[66:67], v[48:49], 0, v[162:163]
	v_lshl_add_u64 v[48:49], v[136:137], 0, v[52:53]
	global_load_dwordx4 v[10:13], v[14:15], off
	s_nop 0
	global_load_dwordx4 v[14:17], v[14:15], off offset:64
	s_nop 0
	global_load_dwordx4 v[18:21], v[22:23], off
	s_nop 0
	global_load_dwordx4 v[22:25], v[22:23], off offset:64
	s_nop 0
	global_load_dwordx4 v[26:29], v[30:31], off
	s_nop 0
	global_load_dwordx4 v[30:33], v[30:31], off offset:64
	s_nop 0
	global_load_dwordx4 v[34:37], v[38:39], off
	s_nop 0
	global_load_dwordx4 v[38:41], v[38:39], off offset:64
	s_nop 0
	global_load_dwordx2 v[42:43], v[50:51], off
	global_load_dwordx2 v[44:45], v[64:65], off
	global_load_dwordx2 v[46:47], v[50:51], off offset:1024
	s_nop 0
	global_load_dwordx2 v[50:51], v[50:51], off offset:2048
	v_lshl_add_u64 v[68:69], v[48:49], 0, v[62:63]
	global_load_dwordx2 v[48:49], v[64:65], off offset:1024
	global_load_dwordx2 v[52:53], v[64:65], off offset:2048
	global_load_dwordx2 v[62:63], v[66:67], off
	s_nop 0
	global_load_dwordx2 v[64:65], v[68:69], off
	v_add_u32_e32 v66, 0x10c0, v70
	v_ashrrev_i32_e32 v66, 5, v66
	v_add_u32_e32 v68, 0x10d0, v70
	v_ashrrev_i32_e32 v67, 31, v66
	v_lshlrev_b64 v[72:73], 12, v[66:67]
	v_ashrrev_i32_e32 v66, 5, v68
	v_ashrrev_i32_e32 v67, 31, v66
	v_lshlrev_b64 v[76:77], 12, v[66:67]
	v_lshl_add_u64 v[66:67], v[134:135], 0, v[72:73]
	v_lshl_add_u64 v[72:73], v[136:137], 0, v[72:73]
	v_lshl_add_u64 v[74:75], v[66:67], 0, v[162:163]
	v_lshl_add_u64 v[78:79], v[138:139], 0, v[76:77]
	v_lshl_add_u64 v[80:81], v[72:73], 0, v[162:163]
	global_load_dwordx2 v[66:67], v[74:75], off
	global_load_dwordx2 v[68:69], v[78:79], off
	global_load_dwordx2 v[70:71], v[74:75], off offset:1024
	s_nop 0
	global_load_dwordx2 v[74:75], v[74:75], off offset:2048
	v_lshl_add_u64 v[166:167], v[140:141], 0, v[76:77]
	global_load_dwordx2 v[72:73], v[78:79], off offset:1024
	global_load_dwordx2 v[76:77], v[78:79], off offset:2048
	s_nop 0
	global_load_dwordx2 v[78:79], v[80:81], off
	s_nop 0
	global_load_dwordx2 v[80:81], v[166:167], off
.LBB0_356:
	v_add_f32_e32 v162, 0, v176
	v_add_f32_e32 v162, v177, v162
	v_add_f32_e32 v116, 0, v116
	v_add_f32_e32 v162, v178, v162
	v_add_f32_e32 v116, v117, v116
	v_add_f32_e32 v162, v179, v162
	v_add_f32_e32 v116, v118, v116
	v_add_f32_e32 v162, v180, v162
	v_add_f32_e32 v116, v119, v116
	v_add_f32_e32 v162, v181, v162
	v_add_f32_e32 v116, v120, v116
	v_add_f32_e32 v162, v182, v162
	v_add_f32_e32 v116, v121, v116
	v_add_f32_e32 v162, v183, v162
	v_add_f32_e32 v116, v122, v116
	v_add_f32_e32 v162, v184, v162
	v_add_f32_e32 v116, v123, v116
	v_add_f32_e32 v162, v185, v162
	v_add_f32_e32 v116, v124, v116
	v_add_f32_e32 v162, v186, v162
	v_add_f32_e32 v116, v125, v116
	v_add_f32_e32 v162, v187, v162
	v_add_f32_e32 v116, v126, v116
	v_add_f32_e32 v162, v188, v162
	v_add_f32_e32 v116, v127, v116
	v_add_f32_e32 v162, v189, v162
	v_add_f32_e32 v116, v128, v116
	v_add_f32_e32 v162, v190, v162
	v_add_f32_e32 v116, v129, v116
	v_add_f32_e32 v162, v191, v162
	v_add_f32_e32 v116, v227, v116
	v_fmac_f32_e32 v162, v147, v142
	v_add_f32_e32 v147, v228, v116
	v_fmac_f32_e32 v147, v162, v114
	v_add_f32_e32 v114, 0, v193
	v_add_f32_e32 v114, v212, v114
	v_add_f32_e32 v114, v213, v114
	v_add_f32_e32 v114, v214, v114
	v_add_f32_e32 v114, v215, v114
	v_add_f32_e32 v114, v216, v114
	v_add_f32_e32 v114, v217, v114
	v_add_f32_e32 v114, v218, v114
	v_add_f32_e32 v114, v219, v114
	v_add_f32_e32 v114, v220, v114
	v_add_f32_e32 v114, v221, v114
	v_add_f32_e32 v114, v222, v114
	v_add_f32_e32 v114, v223, v114
	v_add_f32_e32 v114, v224, v114
	v_add_f32_e32 v114, v225, v114
	v_add_f32_e32 v114, v226, v114
	v_fmac_f32_e32 v114, v175, v144
	s_addk_i32 s3, 0x80
	v_add_u32_e32 v148, 0xf8, v148
	v_add_u32_e32 v149, 0xf8, v149
	v_add_u32_e32 v150, 0xf8, v150
	v_add_u32_e32 v151, 0xf8, v151
	v_add_u32_e32 v152, 0xf8, v152
	v_add_u32_e32 v153, 0xf8, v153
	v_add_u32_e32 v154, 0xf8, v154
	v_add_u32_e32 v155, 0xf8, v155
	v_add_u32_e32 v156, 0x80, v156
	v_add_u32_e32 v157, 0x80, v157
	v_add_u32_e32 v160, 0x2000, v160
	s_cmpk_lg_i32 s3, 0x200
	v_add_u32_e32 v161, 0x2000, v161
	s_cbranch_scc0 .LBB0_320
	v_mov_b32_e32 v175, v114
	s_branch .LBB0_324
.LBB0_360:
	v_readlane_b32 s0, v253, 0
	s_barrier
	s_cmpk_gt_i32 s0, 0x7ff
	s_cbranch_scc1 .LBB0_403
	v_readlane_b32 s8, v254, 36
	v_readlane_b32 s9, v254, 37
	v_readlane_b32 s12, v254, 40
	v_readlane_b32 s13, v254, 41
	s_mul_i32 s2, s82, 0x1800
	s_mov_b64 s[8:9], s[12:13]
	s_mul_hi_i32 s1, s82, 0x1800
	s_add_u32 s2, s8, s2
	s_addc_u32 s3, s9, s1
	s_lshl_b32 s1, s0, 3
	s_addk_i32 s1, 0xe000
	v_readlane_b32 s10, v254, 38
	v_readlane_b32 s11, v254, 39
	v_readlane_b32 s14, v254, 42
	v_readlane_b32 s15, v254, 43
	v_lshrrev_b32_e32 v244, 6, v1
	s_nop 0
	v_readfirstlane_b32 s6, v244
	v_and_b32_e32 v244, 63, v1
	v_lshlrev_b32_e32 v245, 5, v244
	v_lshlrev_b32_e32 v244, 4, v244
	v_add_u32_e32 v246, 0x1000, v245
	global_load_dwordx4 v[174:177], v245, s[2:3]
	global_load_dwordx4 v[178:181], v245, s[2:3] offset:16
	global_load_dwordx4 v[182:185], v245, s[2:3] offset:2048
	global_load_dwordx4 v[186:189], v245, s[2:3] offset:2064
	global_load_dwordx4 v[190:193], v246, s[2:3]
	global_load_dwordx4 v[240:243], v246, s[2:3] offset:16
	s_mov_b32 s8, s0
